# P0: waves 4-7 run rmsnorm rows first and weight transposes after (waves 0-3 original order) so bandwidth-bound and latency-bound work overlap
# baseline (speedup 1.0000x reference)
.LBB0_5:
	s_or_b64 exec, exec, s[0:1]
	s_add_u32 s82, s76, 0x200000
	s_addc_u32 s83, s77, 0
	s_add_u32 s0, s76, 0xf00000
	s_addc_u32 s1, s77, 0
	s_add_u32 s58, s76, 0x1100000
	s_addc_u32 s59, s77, 0
	s_add_u32 s4, s76, 0x1300000
	s_addc_u32 s5, s77, 0
	v_writelane_b32 v254, s4, 6
	s_mov_b32 s33, 1
	s_nop 0
	v_writelane_b32 v254, s5, 7
	s_add_u32 s4, s76, 0x1e00000
	s_addc_u32 s5, s77, 0
	v_writelane_b32 v254, s4, 8
	s_nop 1
	v_writelane_b32 v254, s5, 9
	s_add_u32 s4, s76, 0x2400000
	s_addc_u32 s5, s77, 0
	v_writelane_b32 v254, s4, 10
	s_cmp_lt_i32 s78, 1
	s_nop 0
	v_writelane_b32 v254, s5, 11
	s_cselect_b64 s[4:5], -1, 0
	s_cmp_gt_i32 s79, 0
	s_cselect_b64 s[6:7], -1, 0
	s_and_b64 s[4:5], s[4:5], s[6:7]
	s_andn2_b64 vcc, exec, s[4:5]
	s_cbranch_vccnz .LBB0_139
	v_readfirstlane_b32 s98, v214
	s_bfe_u32 s98, s98, 0x10008
.Lp0_b6:
	v_mov_b32_e32 v7, v214
	s_mov_b32 s34, s73
	v_readfirstlane_b32 s4, v7
	s_mov_b32 s35, s69
	s_ashr_i32 s7, s4, 6
	s_lshl_b32 s31, s35, 3
	v_and_b32_e32 v23, 63, v7
	s_lshl_b32 s6, s34, 3
	s_add_i32 s30, s31, s7
	v_and_b32_e32 v44, 31, v7
	v_lshlrev_b32_e32 v2, 3, v23
	s_cmp_lg_u32 s98, 1
	s_cbranch_scc1 .Lp0_norm
	s_mov_b32 s98, 2
	s_branch .Lp0_rms_test
.Lp0_norm:
	s_cmpk_gt_i32 s30, 0x217f
	s_cbranch_scc1 .LBB0_62
	v_readlane_b32 s26, v254, 0
	v_and_b32_e32 v1, 56, v2
	v_readlane_b32 s8, v254, 8
	v_readlane_b32 s27, v254, 1
	v_lshlrev_b32_e32 v8, 1, v1
	v_mov_b32_e32 v9, 0
	v_readlane_b32 s9, v254, 9
	s_lshl_b32 s16, s7, 14
	v_lshrrev_b32_e32 v45, 3, v23
	v_lshl_add_u64 v[10:11], s[8:9], 0, v[8:9]
	s_load_dwordx4 s[8:11], s[26:27], 0x50
	s_load_dwordx2 s[20:21], s[26:27], 0x40
	s_add_i32 s4, s16, 0
	s_load_dwordx2 s[18:19], s[26:27], 0x70
	v_lshlrev_b32_e32 v3, 2, v44
	v_mul_u32_u24_e32 v5, 0x84, v1
	v_lshlrev_b32_e32 v1, 2, v45
	s_load_dwordx2 s[24:25], s[26:27], 0x10
	s_load_dwordx4 s[12:15], s[26:27], 0x30
	v_lshrrev_b32_e32 v4, 5, v23
	v_add_u32_e32 v6, s4, v3
	v_add3_u32 v46, s4, v5, v1
	v_readlane_b32 s4, v254, 6
	v_readlane_b32 s5, v254, 7
	v_mul_u32_u24_e32 v5, 0x84, v4
	s_waitcnt lgkmcnt(0)
	s_cmp_lg_u64 s[8:9], 0
	v_lshl_add_u64 v[12:13], s[4:5], 0, v[8:9]
	v_lshl_add_u64 v[16:17], s[76:77], 0, v[8:9]
	s_mov_b64 s[4:5], 0xf00400
	v_or_b32_e32 v5, s16, v5
	s_mov_b32 s17, 0
	s_movk_i32 s36, 0x84
	v_or_b32_e32 v47, 8, v45
	v_or_b32_e32 v48, 16, v45
	v_or_b32_e32 v49, 24, v45
	s_cselect_b64 s[22:23], -1, 0
	v_lshl_add_u64 v[14:15], s[58:59], 0, v[8:9]
	v_lshl_add_u64 v[16:17], v[16:17], 0, s[4:5]
	v_lshl_add_u64 v[18:19], s[0:1], 0, v[8:9]
	v_lshl_add_u64 v[20:21], s[82:83], 0, v[8:9]
	v_mov_b32_e32 v1, v4
	v_add3_u32 v50, v5, v3, 0
	v_or_b32_e32 v51, 14, v4
	v_lshlrev_b32_e32 v22, 2, v4
	v_mov_b32_e32 v3, v9
	v_or_b32_e32 v52, 12, v4
	v_or_b32_e32 v53, 10, v4
	v_or_b32_e32 v54, 8, v4
	v_or_b32_e32 v55, 6, v4
	v_or_b32_e32 v56, 4, v4
	v_or_b32_e32 v57, 2, v4
	s_movk_i32 s37, 0x5800
	s_movk_i32 s38, 0x3ff
	s_movk_i32 s39, 0x6800
	s_mov_b32 s40, s30
	s_branch .LBB0_9

.LBB0_68:
	s_or_b64 exec, exec, s[8:9]
	s_cmp_eq_u32 s98, 3
	s_cbranch_scc1 .Lp0_end
.Lp0_rms_test:
	s_cmpk_gt_i32 s30, 0x7fff
	s_cbranch_scc1 .LBB0_71
	v_mbcnt_lo_u32_b32 v1, -1, 0
	v_mbcnt_hi_u32_b32 v3, -1, v1
	v_and_b32_e32 v1, 64, v3
	v_add_u32_e32 v4, 64, v1
	v_xor_b32_e32 v1, 1, v3
	v_cmp_lt_i32_e32 vcc, v1, v4
	v_xor_b32_e32 v5, 2, v3
	v_readlane_b32 s4, v254, 0
	v_cndmask_b32_e32 v1, v3, v1, vcc
	v_cmp_lt_i32_e32 vcc, v5, v4
	v_readlane_b32 s5, v254, 1
	s_load_dwordx4 s[12:15], s[4:5], 0x0
	s_nop 0
	s_load_dwordx2 s[4:5], s[4:5], 0x48
	v_cndmask_b32_e32 v5, v3, v5, vcc
	v_lshlrev_b32_e32 v11, 2, v5
	v_xor_b32_e32 v5, 4, v3
	v_cmp_lt_i32_e32 vcc, v5, v4
	v_readlane_b32 s8, v254, 10
	v_readlane_b32 s9, v254, 11
	v_cndmask_b32_e32 v5, v3, v5, vcc
	v_lshlrev_b32_e32 v12, 2, v5
	v_xor_b32_e32 v5, 8, v3
	v_cmp_lt_i32_e32 vcc, v5, v4
	v_lshlrev_b32_e32 v6, 4, v23
	v_lshlrev_b32_e32 v1, 2, v1
	v_cndmask_b32_e32 v5, v3, v5, vcc
	v_lshlrev_b32_e32 v13, 2, v5
	v_xor_b32_e32 v5, 16, v3
	v_cmp_lt_i32_e32 vcc, v5, v4
	v_mov_b32_e32 v10, 0x358637bd
	s_nop 0
	v_cndmask_b32_e32 v5, v3, v5, vcc
	v_lshlrev_b32_e32 v14, 2, v5
	v_xor_b32_e32 v5, 32, v3
	v_cmp_lt_i32_e32 vcc, v5, v4
	s_nop 1
	v_cndmask_b32_e32 v3, v3, v5, vcc
	v_lshlrev_b32_e32 v15, 2, v3
	v_mov_b32_e32 v3, 0
	v_mov_b32_e32 v7, v3
	v_lshl_add_u64 v[4:5], s[8:9], 0, v[2:3]
	s_waitcnt lgkmcnt(0)
	v_lshl_add_u64 v[8:9], s[4:5], 0, v[6:7]
	s_ashr_i32 s5, s7, 31
	s_ashr_i32 s8, s31, 31
	s_add_u32 s4, s7, s31
	s_addc_u32 s5, s5, s8
	s_lshl_b64 s[16:17], s[4:5], 12
	s_add_u32 s8, s12, s16
	s_addc_u32 s9, s13, s17
	s_ashr_i32 s7, s6, 31
	s_lshl_b64 s[10:11], s[6:7], 12
	s_lshl_b64 s[4:5], s[4:5], 11
	s_add_u32 s4, s76, s4
	s_addc_u32 s5, s77, s5
	s_lshl_b64 s[12:13], s[6:7], 11
	v_lshl_add_u64 v[2:3], s[4:5], 0, v[2:3]
	s_mov_b64 s[4:5], 0x2400400
	s_add_u32 s14, s14, s16
	v_lshl_add_u64 v[2:3], v[2:3], 0, s[4:5]
	s_addc_u32 s15, s15, s17
	s_mov_b32 s16, 0x3a800000
	s_mov_b32 s7, 0x800000

.LBB0_71:
	s_cmp_lg_u32 s98, 2
	s_cbranch_scc1 .Lp0_end
	s_mov_b32 s98, 3
	s_branch .Lp0_b6
